# hgrn chunk loops: packing of the prefetched next-chunk inputs (and its vmcnt ladder) moved from right after the loads to the loop back-edge
# speedup vs baseline: 1.0076x; 1.0076x over previous
; __device__ __forceinline__ unsigned cvt_pk_bf16(float lo, float hi) { f32x2_t v = {lo, hi}; bf16x2_t b = __builtin_convertvector(v, bf16x2_t); return __builtin_bit_cast(unsigned, b); }
; #define LAS __attribute__((address_space(3)))
; __device__ __forceinline__ float silu_f(float x) { return x * fsigmoid(x); }
; template <bool FULL>
; __device__ __forceinline__ void hgrn_seg(CArgs& a, LAS unsigned char* lds, int layer, int item, const bf16* z, bf16* mix, float* HS, float* HD) {
;     ...
;         { const int t = 16 * tb + fr; const float rs = rsqrtf((red[t] + red[64 + t]) * (1.f / 128.f) + EPS);
;           bf16* mr = mix + (t0 + t) * D + hd * 128;
; #pragma unroll
;           for (int i = 0; i < 4; ++i) { const int v0 = 16 * (vh * 4 + i) + 4 * fq;
;               const u32x2 gw = gwv[i]; const f32x4 gg = ggv[i];
;               const float g0 = __uint_as_float(gw.x << 16), g1 = __uint_as_float(gw.x & 0xffff0000u), g2 = __uint_as_float(gw.y << 16), g3 = __uint_as_float(gw.y & 0xffff0000u);
;               u32x2 w; w.x = cvt_pk_bf16(o[i][0] * rs * gg[0] * silu_f(g0), o[i][1] * rs * gg[1] * silu_f(g1));
;               w.y = cvt_pk_bf16(o[i][2] * rs * gg[2] * silu_f(g2), o[i][3] * rs * gg[3] * silu_f(g3));
;               *(u32x2*)(mr + v0) = w; } }
;         }
; #pragma unroll
;         for (int kb = 0; kb < 8; ++kb) { const f32x4 d4 = *(const LAS f32x4*)(dk + 16 * kb + 4 * fq);
;             st[kb] = st[kb] * d4;
;             st[kb] = mma16<2>(VT + 16 * wave * SLD, SLD, KsT + 16 * kb * SLD, SLD, st[kb], fr, fq);
;             if (FULL) { u32x2 w; w.x = cvt_pk_bf16(st[kb][0], st[kb][1]); w.y = cvt_pk_bf16(st[kb][2], st[kb][3]);
;                 *(LAS u32x2*)(StT + (16 * wave + fr) * QLD + 16 * kb + 4 * fq) = w; } }
.LBB0_125:
	s_or_b64 exec, exec, vcc
	s_waitcnt lgkmcnt(0)
	s_barrier
	ds_read2st64_b32 v[78:79], v147 offset1:1
	s_add_u32 s54, s54, 0x60000
	s_addc_u32 s55, s55, 0
	s_mov_b64 s[74:75], 0x20000
	s_cmp_lg_u32 s54, 0x300000
	s_waitcnt lgkmcnt(0)
	v_add_f32_e32 v0, v78, v79
	v_fmamk_f32 v0, v0, 0x3c000000, v142
	v_cmp_gt_f32_e32 vcc, s72, v0
	v_mul_f32_e32 v77, 0x4b800000, v0
	s_waitcnt vmcnt(3)
	v_lshlrev_b32_e32 v78, 16, v112
	v_cndmask_b32_e32 v0, v0, v77, vcc
	v_rsq_f32_e32 v0, v0
	v_and_b32_e32 v79, 0xffff0000, v112
	v_mul_f32_e32 v77, 0x45800000, v0
	v_cndmask_b32_e32 v0, v0, v77, vcc
	v_mul_f32_e32 v77, 0xbfb8aa3b, v78
	v_exp_f32_e32 v77, v77
	v_pk_mul_f32 v[68:69], v[68:69], v[0:1] op_sel_hi:[1,0]
	v_pk_mul_f32 v[70:71], v[70:71], v[0:1] op_sel_hi:[1,0]
	v_pk_mul_f32 v[68:69], v[36:37], v[68:69]
	v_add_f32_e32 v77, 1.0, v77
	v_rcp_f32_e32 v80, v77
	v_mul_f32_e32 v77, 0xbfb8aa3b, v79
	v_exp_f32_e32 v77, v77
	v_pk_mul_f32 v[70:71], v[38:39], v[70:71]
	v_pk_mul_f32 v[64:65], v[64:65], v[0:1] op_sel_hi:[1,0]
	v_pk_mul_f32 v[66:67], v[66:67], v[0:1] op_sel_hi:[1,0]
	v_add_f32_e32 v77, 1.0, v77
	v_rcp_f32_e32 v81, v77
	v_pk_mul_f32 v[64:65], v[40:41], v[64:65]
	v_pk_mul_f32 v[66:67], v[42:43], v[66:67]
	v_pk_mul_f32 v[60:61], v[60:61], v[0:1] op_sel_hi:[1,0]
	v_pk_mul_f32 v[78:79], v[80:81], v[78:79]
	v_pk_mul_f32 v[60:61], v[44:45], v[60:61]
	v_pk_mul_f32 v[68:69], v[78:79], v[68:69]
	v_lshlrev_b32_e32 v78, 16, v113
	v_cvt_pk_bf16_f32 v68, v68, v69
	v_mul_f32_e32 v69, 0xbfb8aa3b, v78
	v_exp_f32_e32 v69, v69
	v_and_b32_e32 v79, 0xffff0000, v113
	v_pk_mul_f32 v[62:63], v[62:63], v[0:1] op_sel_hi:[1,0]
	v_add_f32_e32 v69, 1.0, v69
	v_rcp_f32_e32 v80, v69
	v_mul_f32_e32 v69, 0xbfb8aa3b, v79
	v_exp_f32_e32 v69, v69
	v_pk_mul_f32 v[62:63], v[46:47], v[62:63]
	v_add_f32_e32 v69, 1.0, v69
	v_rcp_f32_e32 v81, v69
	s_nop 0
	v_pk_mul_f32 v[78:79], v[80:81], v[78:79]
	s_nop 0
	v_pk_mul_f32 v[70:71], v[78:79], v[70:71]
	s_nop 0
	v_cvt_pk_bf16_f32 v69, v70, v71
	global_store_dwordx2 v[102:103], v[68:69], off offset:-64
	s_waitcnt vmcnt(3)
	v_lshlrev_b32_e32 v68, 16, v110
	v_and_b32_e32 v69, 0xffff0000, v110
	v_mul_f32_e32 v70, 0xbfb8aa3b, v68
	v_mul_f32_e32 v71, 0xbfb8aa3b, v69
	v_exp_f32_e32 v70, v70
	v_exp_f32_e32 v71, v71
	v_add_f32_e32 v70, 1.0, v70
	v_add_f32_e32 v71, 1.0, v71
	v_rcp_f32_e32 v70, v70
	v_rcp_f32_e32 v71, v71
	s_nop 0
	v_pk_mul_f32 v[68:69], v[70:71], v[68:69]
	s_nop 0
	v_pk_mul_f32 v[64:65], v[68:69], v[64:65]
	v_lshlrev_b32_e32 v68, 16, v111
	v_cvt_pk_bf16_f32 v64, v64, v65
	v_mul_f32_e32 v65, 0xbfb8aa3b, v68
	v_exp_f32_e32 v65, v65
	v_and_b32_e32 v69, 0xffff0000, v111
	v_add_f32_e32 v65, 1.0, v65
	v_rcp_f32_e32 v70, v65
	v_mul_f32_e32 v65, 0xbfb8aa3b, v69
	v_exp_f32_e32 v65, v65
	s_nop 0
	v_add_f32_e32 v65, 1.0, v65
	v_rcp_f32_e32 v71, v65
	s_nop 0
	v_pk_mul_f32 v[68:69], v[70:71], v[68:69]
	s_nop 0
	v_pk_mul_f32 v[66:67], v[68:69], v[66:67]
	s_nop 0
	v_cvt_pk_bf16_f32 v65, v66, v67
	global_store_dwordx2 v[102:103], v[64:65], off offset:-32
	s_waitcnt vmcnt(3)
	v_lshlrev_b32_e32 v64, 16, v108
	v_and_b32_e32 v65, 0xffff0000, v108
	v_mul_f32_e32 v66, 0xbfb8aa3b, v64
	v_mul_f32_e32 v67, 0xbfb8aa3b, v65
	v_exp_f32_e32 v66, v66
	v_exp_f32_e32 v67, v67
	v_add_f32_e32 v66, 1.0, v66
	v_add_f32_e32 v67, 1.0, v67
	v_rcp_f32_e32 v66, v66
	v_rcp_f32_e32 v67, v67
	s_nop 0
	v_pk_mul_f32 v[64:65], v[66:67], v[64:65]
	s_nop 0
	v_pk_mul_f32 v[60:61], v[64:65], v[60:61]
	v_lshlrev_b32_e32 v64, 16, v109
	v_cvt_pk_bf16_f32 v60, v60, v61
	v_mul_f32_e32 v61, 0xbfb8aa3b, v64
	v_exp_f32_e32 v61, v61
	v_and_b32_e32 v65, 0xffff0000, v109
	v_add_f32_e32 v61, 1.0, v61
	v_rcp_f32_e32 v66, v61
	v_mul_f32_e32 v61, 0xbfb8aa3b, v65
	v_exp_f32_e32 v61, v61
	s_nop 0
	v_add_f32_e32 v61, 1.0, v61
	v_rcp_f32_e32 v67, v61
	s_nop 0
	v_pk_mul_f32 v[64:65], v[66:67], v[64:65]
	s_nop 0
	v_pk_mul_f32 v[62:63], v[64:65], v[62:63]
	v_pk_mul_f32 v[64:65], v[72:73], v[0:1] op_sel_hi:[1,0]
	v_cvt_pk_bf16_f32 v61, v62, v63
	global_store_dwordx2 v[102:103], v[60:61], off
	s_waitcnt vmcnt(3)
	v_lshlrev_b32_e32 v60, 16, v106
	v_and_b32_e32 v61, 0xffff0000, v106
	v_mul_f32_e32 v62, 0xbfb8aa3b, v60
	v_mul_f32_e32 v63, 0xbfb8aa3b, v61
	v_exp_f32_e32 v62, v62
	v_exp_f32_e32 v63, v63
	v_pk_mul_f32 v[64:65], v[48:49], v[64:65]
	v_pk_mul_f32 v[66:67], v[74:75], v[0:1] op_sel_hi:[1,0]
	v_add_f32_e32 v62, 1.0, v62
	v_add_f32_e32 v63, 1.0, v63
	v_rcp_f32_e32 v62, v62
	v_rcp_f32_e32 v63, v63
	v_pk_mul_f32 v[66:67], v[50:51], v[66:67]
	v_pk_mul_f32 v[60:61], v[62:63], v[60:61]
	s_nop 0
	v_pk_mul_f32 v[60:61], v[60:61], v[64:65]
	v_lshlrev_b32_e32 v62, 16, v107
	v_and_b32_e32 v63, 0xffff0000, v107
	v_cvt_pk_bf16_f32 v60, v60, v61
	v_mul_f32_e32 v61, 0xbfb8aa3b, v62
	v_mul_f32_e32 v0, 0xbfb8aa3b, v63
	v_exp_f32_e32 v61, v61
	v_exp_f32_e32 v0, v0
	v_add_f32_e32 v61, 1.0, v61
	v_add_f32_e32 v0, 1.0, v0
	v_rcp_f32_e32 v64, v61
	v_rcp_f32_e32 v65, v0
	s_nop 0
	v_pk_mul_f32 v[62:63], v[64:65], v[62:63]
	s_nop 0
	v_pk_mul_f32 v[62:63], v[62:63], v[66:67]
	s_nop 0
	v_cvt_pk_bf16_f32 v61, v62, v63
	global_store_dwordx2 v[102:103], v[60:61], off offset:32
	ds_read_b128 v[60:63], v148
	v_lshl_add_u64 v[102:103], v[102:103], 0, s[74:75]
	s_waitcnt lgkmcnt(0)
	v_pk_mul_f32 v[34:35], v[34:35], v[62:63]
	v_pk_mul_f32 v[32:33], v[32:33], v[60:61]
	ds_read_b128 v[60:63], v149 offset:53248
	ds_read_b128 v[64:67], v145 offset:34816
	s_waitcnt lgkmcnt(0)
	v_mfma_f32_16x16x32_bf16 v[32:35], v[64:67], v[60:63], v[32:35]
	ds_read_b128 v[60:63], v149 offset:53312
	ds_read_b128 v[64:67], v145 offset:34880
	s_waitcnt lgkmcnt(0)
; __device__ __forceinline__ unsigned cvt_pk_bf16(float lo, float hi) { f32x2_t v = {lo, hi}; bf16x2_t b = __builtin_convertvector(v, bf16x2_t); return __builtin_bit_cast(unsigned, b); }
; #define LAS __attribute__((address_space(3)))
; #define BLOCK_SYNC() do { asm volatile("s_waitcnt lgkmcnt(0)" ::: "memory"); __builtin_amdgcn_s_barrier(); asm volatile("" ::: "memory"); } while (0)
; template <bool FULL>
; __device__ __forceinline__ void hgrn_seg(CArgs& a, LAS unsigned char* lds, int layer, int item, const bf16* z, bf16* mix, float* HS, float* HD) {
;     ...
;             ksp[j >> 1] = cvt_pk_bf16(ks2[0], ks2[1]); vip[j >> 1] = (unsigned)ri[j] | ((unsigned)ri[j + 1] << 16);
;     ...
; #pragma unroll
;         for (int kb = 0; kb < 8; ++kb) { const f32x4 d4 = *(const LAS f32x4*)(dk + 16 * kb + 4 * fq);
;             st[kb] = st[kb] * d4;
;             st[kb] = mma16<2>(VT + 16 * wave * SLD, SLD, KsT + 16 * kb * SLD, SLD, st[kb], fr, fq);
;             if (FULL) { u32x2 w; w.x = cvt_pk_bf16(st[kb][0], st[kb][1]); w.y = cvt_pk_bf16(st[kb][2], st[kb][3]);
;                 *(LAS u32x2*)(StT + (16 * wave + fr) * QLD + 16 * kb + 4 * fq) = w; } }
;         BLOCK_SYNC();
	v_mfma_f32_16x16x32_bf16 v[32:35], v[64:67], v[60:63], v[32:35]
	s_nop 7
	v_cvt_pk_bf16_f32 v60, v32, v33
	v_cvt_pk_bf16_f32 v61, v34, v35
	ds_write_b64 v150, v[60:61]
	ds_read_b128 v[60:63], v148 offset:64
	s_waitcnt lgkmcnt(0)
	v_pk_mul_f32 v[6:7], v[6:7], v[62:63]
	v_pk_mul_f32 v[4:5], v[4:5], v[60:61]
	ds_read_b128 v[60:63], v149 offset:53248
	ds_read_b128 v[64:67], v145 offset:37120
	s_waitcnt lgkmcnt(0)
	v_mfma_f32_16x16x32_bf16 v[4:7], v[64:67], v[60:63], v[4:7]
	ds_read_b128 v[60:63], v149 offset:53312
	ds_read_b128 v[64:67], v145 offset:37184
	s_waitcnt lgkmcnt(0)
	v_mfma_f32_16x16x32_bf16 v[4:7], v[64:67], v[60:63], v[4:7]
	s_nop 7
	v_cvt_pk_bf16_f32 v60, v4, v5
	v_cvt_pk_bf16_f32 v61, v6, v7
	ds_write_b64 v150, v[60:61] offset:32
	ds_read_b128 v[60:63], v148 offset:128
	s_waitcnt lgkmcnt(0)
	v_pk_mul_f32 v[10:11], v[10:11], v[62:63]
	v_pk_mul_f32 v[8:9], v[8:9], v[60:61]
	ds_read_b128 v[60:63], v149 offset:53248
	ds_read_b128 v[64:67], v145 offset:39424
	s_waitcnt lgkmcnt(0)
	v_mfma_f32_16x16x32_bf16 v[8:11], v[64:67], v[60:63], v[8:11]
	ds_read_b128 v[60:63], v149 offset:53312
	ds_read_b128 v[64:67], v145 offset:39488
	s_waitcnt lgkmcnt(0)
	v_mfma_f32_16x16x32_bf16 v[8:11], v[64:67], v[60:63], v[8:11]
	s_nop 7
	v_cvt_pk_bf16_f32 v60, v8, v9
	v_cvt_pk_bf16_f32 v61, v10, v11
	ds_write_b64 v150, v[60:61] offset:64
	ds_read_b128 v[60:63], v148 offset:192
	s_waitcnt lgkmcnt(0)
	v_pk_mul_f32 v[14:15], v[14:15], v[62:63]
	v_pk_mul_f32 v[12:13], v[12:13], v[60:61]
	ds_read_b128 v[60:63], v149 offset:53248
	ds_read_b128 v[64:67], v145 offset:41728
	s_waitcnt lgkmcnt(0)
	v_mfma_f32_16x16x32_bf16 v[12:15], v[64:67], v[60:63], v[12:15]
	ds_read_b128 v[60:63], v149 offset:53312
	ds_read_b128 v[64:67], v145 offset:41792
	s_waitcnt lgkmcnt(0)
	v_mfma_f32_16x16x32_bf16 v[12:15], v[64:67], v[60:63], v[12:15]
	s_nop 7
	v_cvt_pk_bf16_f32 v60, v12, v13
	v_cvt_pk_bf16_f32 v61, v14, v15
	ds_write_b64 v150, v[60:61] offset:96
	ds_read_b128 v[60:63], v148 offset:256
	s_waitcnt lgkmcnt(0)
	v_pk_mul_f32 v[18:19], v[18:19], v[62:63]
	v_pk_mul_f32 v[16:17], v[16:17], v[60:61]
	ds_read_b128 v[60:63], v149 offset:53248
	ds_read_b128 v[64:67], v145 offset:44032
	s_waitcnt lgkmcnt(0)
	v_mfma_f32_16x16x32_bf16 v[16:19], v[64:67], v[60:63], v[16:19]
	ds_read_b128 v[60:63], v149 offset:53312
	ds_read_b128 v[64:67], v145 offset:44096
	s_waitcnt lgkmcnt(0)
	v_mfma_f32_16x16x32_bf16 v[16:19], v[64:67], v[60:63], v[16:19]
	s_nop 7
	v_cvt_pk_bf16_f32 v60, v16, v17
	v_cvt_pk_bf16_f32 v61, v18, v19
	ds_write_b64 v150, v[60:61] offset:128
	ds_read_b128 v[60:63], v148 offset:320
	s_waitcnt lgkmcnt(0)
	v_pk_mul_f32 v[22:23], v[22:23], v[62:63]
	v_pk_mul_f32 v[20:21], v[20:21], v[60:61]
	ds_read_b128 v[60:63], v149 offset:53248
	ds_read_b128 v[64:67], v145 offset:46336
	s_waitcnt lgkmcnt(0)
	v_mfma_f32_16x16x32_bf16 v[20:23], v[64:67], v[60:63], v[20:23]
	ds_read_b128 v[60:63], v149 offset:53312
	ds_read_b128 v[64:67], v145 offset:46400
	s_waitcnt lgkmcnt(0)
	v_mfma_f32_16x16x32_bf16 v[20:23], v[64:67], v[60:63], v[20:23]
	s_nop 7
	v_cvt_pk_bf16_f32 v60, v20, v21
	v_cvt_pk_bf16_f32 v61, v22, v23
	ds_write_b64 v150, v[60:61] offset:160
	ds_read_b128 v[60:63], v148 offset:384
	s_waitcnt lgkmcnt(0)
	v_pk_mul_f32 v[26:27], v[26:27], v[62:63]
	v_pk_mul_f32 v[24:25], v[24:25], v[60:61]
	ds_read_b128 v[60:63], v149 offset:53248
	ds_read_b128 v[64:67], v145 offset:48640
	s_waitcnt lgkmcnt(0)
	v_mfma_f32_16x16x32_bf16 v[24:27], v[64:67], v[60:63], v[24:27]
	ds_read_b128 v[60:63], v149 offset:53312
	ds_read_b128 v[64:67], v145 offset:48704
	s_waitcnt lgkmcnt(0)
	v_mfma_f32_16x16x32_bf16 v[24:27], v[64:67], v[60:63], v[24:27]
	s_nop 7
	v_cvt_pk_bf16_f32 v60, v24, v25
	v_cvt_pk_bf16_f32 v61, v26, v27
	ds_write_b64 v150, v[60:61] offset:192
	ds_read_b128 v[60:63], v148 offset:448
	s_waitcnt lgkmcnt(0)
	v_pk_mul_f32 v[30:31], v[30:31], v[62:63]
	v_pk_mul_f32 v[28:29], v[28:29], v[60:61]
	ds_read_b128 v[60:63], v149 offset:53248
	ds_read_b128 v[64:67], v145 offset:50944
	s_waitcnt lgkmcnt(0)
	v_mfma_f32_16x16x32_bf16 v[28:31], v[64:67], v[60:63], v[28:31]
	ds_read_b128 v[60:63], v149 offset:53312
	ds_read_b128 v[64:67], v145 offset:51008
	s_waitcnt lgkmcnt(0)
	v_mfma_f32_16x16x32_bf16 v[28:31], v[64:67], v[60:63], v[28:31]
	s_nop 7
	v_cvt_pk_bf16_f32 v60, v28, v29
	v_cvt_pk_bf16_f32 v61, v30, v31
	ds_write_b64 v150, v[60:61] offset:224
	s_waitcnt lgkmcnt(0)
	s_barrier
	s_cbranch_scc0 .LBB0_118
	s_waitcnt vmcnt(8)
	v_lshl_or_b32 v52, v217, 16, v216
	v_lshl_or_b32 v53, v219, 16, v218
	v_lshl_or_b32 v54, v221, 16, v220
	v_lshl_or_b32 v55, v223, 16, v222
	v_lshl_or_b32 v56, v225, 16, v224
	v_lshl_or_b32 v57, v227, 16, v226
	v_lshl_or_b32 v58, v229, 16, v228
	v_lshl_or_b32 v59, v231, 16, v230
; __device__ __forceinline__ float bf2f(unsigned short h) { return __uint_as_float((unsigned)h << 16); }
; #define BLOCK_SYNC() do { asm volatile("s_waitcnt lgkmcnt(0)" ::: "memory"); __builtin_amdgcn_s_barrier(); asm volatile("" ::: "memory"); } while (0)
; template <bool FULL>
; __device__ __forceinline__ void hgrn_seg(CArgs& a, LAS unsigned char* lds, int layer, int item, const bf16* z, bf16* mix, float* HS, float* HD) {
;     ...
;     for (int c = 0; c < SEG_CHUNKS; ++c) {
;         const size_t t0 = tseg + c * 64;
;         float bl[16], kv[16]; float run = 1.f;
; #pragma unroll
;         for (int j = 0; j < 16; ++j) { const float x = fminf(fmaxf(bf2f(rf[j]), -30.f), 30.f); const float e = __expf(-x), sg = __builtin_amdgcn_rcpf(1.f + e);
;             const float f = lb + oml * sg; run *= f; bl[j] = run; kv[j] = oml * e * sg; }
;         seg[tq * 128 + ch] = run;
;         BLOCK_SYNC();
.LBB0_126:
	s_waitcnt vmcnt(24)
	v_lshlrev_b32_e32 v0, 16, v117
	v_max_f32_e32 v0, v0, v0
	v_med3_f32 v0, v0, s0, v166
	v_mul_f32_e32 v0, 0xbfb8aa3b, v0
	v_exp_f32_e32 v95, v0
	s_nop 0
	v_add_f32_e32 v0, 1.0, v95
	v_rcp_f32_e32 v92, v0
	v_lshlrev_b32_e32 v0, 16, v116
	v_max_f32_e32 v0, v0, v0
	v_med3_f32 v0, v0, s0, v166
	v_mul_f32_e32 v0, 0xbfb8aa3b, v0
	v_exp_f32_e32 v79, v0
	v_mov_b32_e32 v209, v92
	v_add_f32_e32 v0, 1.0, v79
	v_rcp_f32_e32 v93, v0
	v_lshlrev_b32_e32 v0, 16, v114
	v_max_f32_e32 v0, v0, v0
	v_med3_f32 v0, v0, s0, v166
	v_mul_f32_e32 v0, 0xbfb8aa3b, v0
	v_exp_f32_e32 v88, v0
	v_pk_fma_f32 v[106:107], v[98:99], v[92:93], v[2:3]
	v_add_f32_e32 v0, 1.0, v88
	v_rcp_f32_e32 v61, v0
	v_mov_b32_e32 v96, v106
	v_mov_b32_e32 v60, v107
	v_pk_mul_f32 v[90:91], v[96:97], v[60:61]
	s_nop 0
	v_add_f32_e32 v0, v2, v91
	v_mul_f32_e32 v203, v90, v0
	v_lshlrev_b32_e32 v0, 16, v120
	v_max_f32_e32 v0, v0, v0
	v_med3_f32 v0, v0, s0, v166
	v_mul_f32_e32 v0, 0xbfb8aa3b, v0
	v_exp_f32_e32 v89, v0
	s_nop 0
	v_add_f32_e32 v0, 1.0, v89
	v_rcp_f32_e32 v91, v0
	v_pk_mul_f32 v[88:89], v[98:99], v[88:89]
	v_fma_f32 v0, v97, v91, v2
	v_mul_f32_e32 v204, v203, v0
	s_waitcnt vmcnt(20)
	v_lshlrev_b32_e32 v0, 16, v121
	v_max_f32_e32 v0, v0, v0
	v_med3_f32 v0, v0, s0, v166
	v_mul_f32_e32 v0, 0xbfb8aa3b, v0
	v_exp_f32_e32 v86, v0
	s_nop 0
	v_add_f32_e32 v0, 1.0, v86
	v_rcp_f32_e32 v62, v0
	s_nop 0
	v_fma_f32 v0, v97, v62, v2
	v_mul_f32_e32 v202, v204, v0
	s_waitcnt vmcnt(14)
	v_lshlrev_b32_e32 v0, 16, v172
	v_max_f32_e32 v0, v0, v0
	v_med3_f32 v0, v0, s0, v166
	v_mul_f32_e32 v0, 0xbfb8aa3b, v0
	v_exp_f32_e32 v87, v0
	s_nop 0
	v_add_f32_e32 v0, 1.0, v87
	v_rcp_f32_e32 v63, v0
	v_pk_mul_f32 v[86:87], v[98:99], v[86:87]
	v_fma_f32 v0, v97, v63, v2
	v_mul_f32_e32 v201, v202, v0
	v_lshlrev_b32_e32 v0, 16, v153
	v_max_f32_e32 v0, v0, v0
	v_med3_f32 v0, v0, s0, v166
	v_mul_f32_e32 v0, 0xbfb8aa3b, v0
	v_exp_f32_e32 v82, v0
	v_pk_mul_f32 v[62:63], v[86:87], v[62:63]
	v_add_f32_e32 v0, 1.0, v82
	v_rcp_f32_e32 v84, v0
	s_nop 0
	v_fma_f32 v0, v97, v84, v2
	v_mul_f32_e32 v200, v201, v0
	s_waitcnt vmcnt(13)
	v_lshlrev_b32_e32 v0, 16, v173
	v_max_f32_e32 v0, v0, v0
	v_med3_f32 v0, v0, s0, v166
	v_mul_f32_e32 v0, 0xbfb8aa3b, v0
	v_exp_f32_e32 v83, v0
	s_nop 0
	v_add_f32_e32 v0, 1.0, v83
	v_rcp_f32_e32 v85, v0
	v_pk_mul_f32 v[82:83], v[98:99], v[82:83]
	v_fma_f32 v0, v97, v85, v2
	v_mul_f32_e32 v199, v200, v0
	v_lshlrev_b32_e32 v0, 16, v182
	v_max_f32_e32 v0, v0, v0
	v_med3_f32 v0, v0, s0, v166
	v_mul_f32_e32 v0, 0xbfb8aa3b, v0
	v_exp_f32_e32 v80, v0
	v_pk_mul_f32 v[82:83], v[82:83], v[84:85]
	v_add_f32_e32 v0, 1.0, v80
	v_rcp_f32_e32 v64, v0
	s_nop 0
	v_fma_f32 v0, v97, v64, v2
	v_mul_f32_e32 v198, v199, v0
	s_waitcnt vmcnt(12)
	v_lshlrev_b32_e32 v0, 16, v186
	v_max_f32_e32 v0, v0, v0
	v_med3_f32 v0, v0, s0, v166
	v_mul_f32_e32 v0, 0xbfb8aa3b, v0
	v_exp_f32_e32 v81, v0
	s_nop 0
	v_add_f32_e32 v0, 1.0, v81
	v_rcp_f32_e32 v65, v0
	v_pk_mul_f32 v[80:81], v[98:99], v[80:81]
	v_fma_f32 v0, v97, v65, v2
	v_mul_f32_e32 v113, v198, v0
	v_lshlrev_b32_e32 v0, 16, v183
	v_max_f32_e32 v0, v0, v0
	v_med3_f32 v0, v0, s0, v166
	v_mul_f32_e32 v0, 0xbfb8aa3b, v0
	v_exp_f32_e32 v76, v0
	v_pk_mul_f32 v[64:65], v[80:81], v[64:65]
	v_add_f32_e32 v0, 1.0, v76
	v_rcp_f32_e32 v74, v0
	s_nop 0
	v_fma_f32 v0, v97, v74, v2
	v_mul_f32_e32 v112, v113, v0
	s_waitcnt vmcnt(11)
	v_lshlrev_b32_e32 v0, 16, v188
	v_max_f32_e32 v0, v0, v0
	v_med3_f32 v0, v0, s0, v166
	v_mul_f32_e32 v0, 0xbfb8aa3b, v0
	v_exp_f32_e32 v77, v0
	s_nop 0
	v_add_f32_e32 v0, 1.0, v77
	v_rcp_f32_e32 v75, v0
	v_pk_mul_f32 v[76:77], v[98:99], v[76:77]
	v_fma_f32 v0, v97, v75, v2
	v_mul_f32_e32 v111, v112, v0
	s_waitcnt vmcnt(4)
	v_lshlrev_b32_e32 v0, 16, v189
	v_max_f32_e32 v0, v0, v0
	v_med3_f32 v0, v0, s0, v166
	v_mul_f32_e32 v0, 0xbfb8aa3b, v0
	v_exp_f32_e32 v66, v0
	v_pk_mul_f32 v[74:75], v[76:77], v[74:75]
	v_add_f32_e32 v0, 1.0, v66
	v_rcp_f32_e32 v72, v0
	s_nop 0
	v_fma_f32 v0, v97, v72, v2
	v_mul_f32_e32 v110, v111, v0
	s_waitcnt vmcnt(1)
	v_lshlrev_b32_e32 v0, 16, v196
	v_max_f32_e32 v0, v0, v0
	v_med3_f32 v0, v0, s0, v166
	v_mul_f32_e32 v0, 0xbfb8aa3b, v0
	v_exp_f32_e32 v67, v0
	s_nop 0
	v_add_f32_e32 v0, 1.0, v67
	v_rcp_f32_e32 v73, v0
	v_pk_mul_f32 v[66:67], v[98:99], v[66:67]
	v_fma_f32 v0, v97, v73, v2
	v_mul_f32_e32 v109, v110, v0
	v_lshlrev_b32_e32 v0, 16, v193
	v_max_f32_e32 v0, v0, v0
	v_med3_f32 v0, v0, s0, v166
	v_mul_f32_e32 v0, 0xbfb8aa3b, v0
	v_exp_f32_e32 v70, v0
	v_pk_mul_f32 v[66:67], v[66:67], v[72:73]
	v_add_f32_e32 v0, 1.0, v70
	v_rcp_f32_e32 v68, v0
	s_nop 0
	v_fma_f32 v0, v97, v68, v2
	v_mul_f32_e32 v107, v109, v0
	v_lshlrev_b32_e32 v0, 16, v194
	v_max_f32_e32 v0, v0, v0
	v_med3_f32 v0, v0, s0, v166
	v_mul_f32_e32 v0, 0xbfb8aa3b, v0
	v_exp_f32_e32 v71, v0
	s_nop 0
	v_add_f32_e32 v0, 1.0, v71
	v_rcp_f32_e32 v69, v0
	v_pk_mul_f32 v[70:71], v[98:99], v[70:71]
	v_fma_f32 v0, v97, v69, v2
	v_mul_f32_e32 v0, v107, v0
	ds_write_b32 v122, v0
	s_waitcnt lgkmcnt(0)
	s_barrier
; __device__ __forceinline__ float fsigmoid(float x) { return __builtin_amdgcn_rcpf(1.0f + __expf(-x)); }
; __device__ __forceinline__ float bf2f(unsigned short h) { return __uint_as_float((unsigned)h << 16); }
; __device__ __forceinline__ unsigned short f2bf(float f) { return (unsigned short)(cvt_pk_bf16(f, 0.f) & 0xffffu); }
; template <bool FULL>
; __device__ __forceinline__ void hgrn_seg(CArgs& a, LAS unsigned char* lds, int layer, int item, const bf16* z, bf16* mix, float* HS, float* HD) {
;     ...
;         float prefix = 1.f, total = 1.f;
; #pragma unroll
;         for (int q = 0; q < 4; ++q) { const float sv = seg[q * 128 + ch]; total *= sv; if (q < tq) prefix *= sv; }
;         dsum *= total;
;         unsigned ksp[8], vip[8];
; #pragma unroll
;         for (int j = 0; j < 16; j += 2) {
;             float ks2[2];
; #pragma unroll
;             for (int jj = 0; jj < 2; ++jj) { const int t = j + jj; const float e1 = fmaxf(prefix * bl[t], 1e-35f), e2 = __builtin_amdgcn_rcpf(e1);
;                 if (FULL) { const float qx = bf2f(rq[t]); const float qv = qx * fsigmoid(qx);
;                     Q[(tq * 16 + t) * QLD + ch] = f2bf(qv * e1);
;                     Kt[(tq * 16 + t) * QLD + ch] = f2bf(kv[t] * e2); }
;                 ks2[jj] = kv[t] * (total * e2); }
	ds_read2st64_b32 v[206:207], v123 offset1:2
	v_pk_mul_f32 v[68:69], v[70:71], v[68:69]
	s_waitcnt lgkmcnt(0)
	v_cndmask_b32_e64 v60, 1.0, v206, s[14:15]
	v_mul_f32_e32 v78, v206, v207
	v_mul_f32_e32 v94, v60, v207
	ds_read2st64_b32 v[206:207], v123 offset0:4 offset1:6
	v_cndmask_b32_e64 v60, v60, v94, s[16:17]
	s_waitcnt lgkmcnt(0)
	v_mul_f32_e32 v96, v78, v206
	v_mul_f32_e32 v78, v206, v60
	v_cndmask_b32_e64 v60, v60, v78, s[18:19]
	v_mul_f32_e32 v78, v207, v60
	v_cndmask_b32_e64 v108, v60, v78, s[20:21]
	v_lshlrev_b32_e32 v78, 16, v119
	v_mul_f32_e32 v94, 0xbfb8aa3b, v78
	v_exp_f32_e32 v94, v94
	v_mul_f32_e32 v60, v106, v108
	v_max_f32_e32 v60, 0x554ad2e, v60
	v_rcp_f32_e32 v206, v60
	v_add_f32_e32 v94, 1.0, v94
	v_rcp_f32_e32 v94, v94
	v_mul_f32_e32 v0, v0, v108
	v_max_f32_e32 v0, 0x554ad2e, v0
	v_mul_f32_e32 v78, v94, v78
	v_mul_f32_e32 v60, v78, v60
	v_cvt_pk_bf16_f32 v60, v60, s0
	v_lshlrev_b32_e32 v78, 16, v118
	ds_write_b16 v151, v60
	v_mul_f32_e32 v60, v90, v108
	v_mul_f32_e32 v90, 0xbfb8aa3b, v78
	v_exp_f32_e32 v90, v90
	v_max_f32_e32 v60, 0x554ad2e, v60
	v_rcp_f32_e32 v208, v60
	v_mov_b32_e32 v94, v207
	v_add_f32_e32 v90, 1.0, v90
	v_rcp_f32_e32 v90, v90
	v_pk_mul_f32 v[94:95], v[96:97], v[94:95]
	v_mul_f32_e32 v78, v90, v78
	v_mul_f32_e32 v60, v78, v60
	v_mov_b32_e32 v78, v207
	v_pk_mul_f32 v[78:79], v[96:97], v[78:79]
	v_mov_b32_e32 v207, v93
	v_cvt_pk_bf16_f32 v60, v60, s0
	v_pk_mul_f32 v[92:93], v[78:79], v[206:207]
	v_pk_mul_f32 v[94:95], v[94:95], v[208:209]
	ds_write_b16 v151, v60 offset:272
	v_mul_f32_e32 v60, v93, v208
	v_cvt_pk_bf16_f32 v60, v60, s0
	v_pk_mul_f32 v[92:93], v[92:93], v[94:95] op_sel:[0,1] op_sel_hi:[1,0]
	ds_write_b16 v151, v60 offset:17680
	v_cvt_pk_bf16_f32 v60, v92, v93
	v_lshlrev_b32_e32 v93, 16, v115
	v_mul_f32_e32 v94, 0xbfb8aa3b, v93
	v_exp_f32_e32 v94, v94
	v_mul_f32_e32 v90, v95, v206
	v_cvt_pk_bf16_f32 v90, v90, s0
	ds_write_b16 v151, v90 offset:17408
	v_add_f32_e32 v94, 1.0, v94
	v_rcp_f32_e32 v94, v94
	v_mul_f32_e32 v90, v203, v108
	v_max_f32_e32 v90, 0x554ad2e, v90
	v_rcp_f32_e32 v92, v90
	v_mul_f32_e32 v93, v94, v93
	v_lshlrev_b32_e32 v94, 16, v127
	v_mul_f32_e32 v95, 0xbfb8aa3b, v94
	v_exp_f32_e32 v95, v95
	v_mul_f32_e32 v90, v93, v90
	v_cvt_pk_bf16_f32 v90, v90, s0
	ds_write_b16 v151, v90 offset:544
	v_add_f32_e32 v95, 1.0, v95
	v_rcp_f32_e32 v95, v95
	v_mul_f32_e32 v90, v204, v108
	v_max_f32_e32 v90, 0x554ad2e, v90
	v_rcp_f32_e32 v93, v90
	v_mul_f32_e32 v94, v95, v94
	v_mul_f32_e32 v90, v94, v90
	v_cvt_pk_bf16_f32 v94, v90, s0
	v_mov_b32_e32 v90, v61
	v_pk_mul_f32 v[88:89], v[88:89], v[90:91]
	v_pk_mul_f32 v[90:91], v[78:79], v[92:93] op_sel_hi:[0,1]
	v_mul_f32_e32 v61, v88, v92
	v_cvt_pk_bf16_f32 v61, v61, s0
	ds_write_b16 v151, v61 offset:17952
	ds_write_b16 v151, v94 offset:816
	v_mul_f32_e32 v61, v89, v93
	v_pk_mul_f32 v[88:89], v[88:89], v[90:91]
	v_lshlrev_b32_e32 v90, 16, v129
	v_mul_f32_e32 v91, 0xbfb8aa3b, v90
	v_exp_f32_e32 v91, v91
	v_cvt_pk_bf16_f32 v61, v61, s0
	ds_write_b16 v151, v61 offset:18224
	v_cvt_pk_bf16_f32 v61, v88, v89
	v_add_f32_e32 v91, 1.0, v91
	v_rcp_f32_e32 v91, v91
	v_mul_f32_e32 v88, v202, v108
	v_max_f32_e32 v89, 0x554ad2e, v88
	v_rcp_f32_e32 v88, v89
	v_mul_f32_e32 v90, v91, v90
	v_lshlrev_b32_e32 v91, 16, v126
	v_mul_f32_e32 v92, 0xbfb8aa3b, v91
	v_exp_f32_e32 v92, v92
	v_mul_f32_e32 v89, v90, v89
	v_cvt_pk_bf16_f32 v89, v89, s0
	ds_write_b16 v151, v89 offset:1088
	v_add_f32_e32 v92, 1.0, v92
	v_mul_f32_e32 v89, v201, v108
	v_rcp_f32_e32 v92, v92
	v_max_f32_e32 v90, 0x554ad2e, v89
	v_rcp_f32_e32 v89, v90
	v_mul_f32_e32 v86, v62, v88
	v_mul_f32_e32 v91, v92, v91
	v_mul_f32_e32 v90, v91, v90
	v_cvt_pk_bf16_f32 v86, v86, s0
	v_cvt_pk_bf16_f32 v90, v90, s0
	ds_write_b16 v151, v86 offset:18496
	ds_write_b16 v151, v90 offset:1360
	v_mul_f32_e32 v86, v63, v89
	v_cvt_pk_bf16_f32 v86, v86, s0
	ds_write_b16 v151, v86 offset:18768
	v_pk_mul_f32 v[86:87], v[78:79], v[88:89] op_sel_hi:[0,1]
	v_pk_mul_f32 v[62:63], v[62:63], v[86:87]
	v_lshlrev_b32_e32 v87, 16, v171
	v_mul_f32_e32 v88, 0xbfb8aa3b, v87
	v_exp_f32_e32 v88, v88
	v_cvt_pk_bf16_f32 v62, v62, v63
	v_mul_f32_e32 v63, v200, v108
	v_max_f32_e32 v63, 0x554ad2e, v63
	v_add_f32_e32 v88, 1.0, v88
	v_rcp_f32_e32 v88, v88
	v_rcp_f32_e32 v86, v63
	v_mul_f32_e32 v87, v88, v87
	v_lshlrev_b32_e32 v88, 16, v175
	v_mul_f32_e32 v89, 0xbfb8aa3b, v88
	v_exp_f32_e32 v89, v89
	v_mul_f32_e32 v63, v87, v63
	v_cvt_pk_bf16_f32 v63, v63, s0
	ds_write_b16 v151, v63 offset:1632
	v_add_f32_e32 v89, 1.0, v89
	v_mul_f32_e32 v63, v199, v108
	v_rcp_f32_e32 v89, v89
	v_max_f32_e32 v63, 0x554ad2e, v63
	v_rcp_f32_e32 v87, v63
	v_mul_f32_e32 v84, v82, v86
	v_mul_f32_e32 v88, v89, v88
	v_mul_f32_e32 v63, v88, v63
	v_cvt_pk_bf16_f32 v84, v84, s0
	v_cvt_pk_bf16_f32 v63, v63, s0
	ds_write_b16 v151, v84 offset:19040
	ds_write_b16 v151, v63 offset:1904
	v_pk_mul_f32 v[84:85], v[78:79], v[86:87] op_sel_hi:[0,1]
	v_mul_f32_e32 v63, v83, v87
	v_pk_mul_f32 v[82:83], v[82:83], v[84:85]
	v_lshlrev_b32_e32 v84, 16, v185
	v_mul_f32_e32 v85, 0xbfb8aa3b, v84
	v_exp_f32_e32 v85, v85
	v_cvt_pk_bf16_f32 v63, v63, s0
	ds_write_b16 v151, v63 offset:19312
	v_cvt_pk_bf16_f32 v63, v82, v83
	v_add_f32_e32 v85, 1.0, v85
	v_rcp_f32_e32 v85, v85
	v_mul_f32_e32 v82, v198, v108
	v_max_f32_e32 v83, 0x554ad2e, v82
	v_rcp_f32_e32 v82, v83
	v_mul_f32_e32 v84, v85, v84
	v_lshlrev_b32_e32 v85, 16, v187
	v_mul_f32_e32 v86, 0xbfb8aa3b, v85
	v_exp_f32_e32 v86, v86
	v_mul_f32_e32 v83, v84, v83
	v_cvt_pk_bf16_f32 v83, v83, s0
	ds_write_b16 v151, v83 offset:2176
	v_add_f32_e32 v86, 1.0, v86
	v_mul_f32_e32 v83, v113, v108
	v_rcp_f32_e32 v86, v86
	v_max_f32_e32 v84, 0x554ad2e, v83
; __device__ __forceinline__ unsigned cvt_pk_bf16(float lo, float hi) { f32x2_t v = {lo, hi}; bf16x2_t b = __builtin_convertvector(v, bf16x2_t); return __builtin_bit_cast(unsigned, b); }
; __device__ __forceinline__ float fsigmoid(float x) { return __builtin_amdgcn_rcpf(1.0f + __expf(-x)); }
; #define LAS __attribute__((address_space(3)))
; __device__ __forceinline__ float bf2f(unsigned short h) { return __uint_as_float((unsigned)h << 16); }
; __device__ __forceinline__ unsigned short f2bf(float f) { return (unsigned short)(cvt_pk_bf16(f, 0.f) & 0xffffu); }
; template <bool FULL>
; __device__ __forceinline__ void hgrn_seg(CArgs& a, LAS unsigned char* lds, int layer, int item, const bf16* z, bf16* mix, float* HS, float* HD) {
;     ...
;         for (int j = 0; j < 16; j += 2) {
;             float ks2[2];
; #pragma unroll
;             for (int jj = 0; jj < 2; ++jj) { const int t = j + jj; const float e1 = fmaxf(prefix * bl[t], 1e-35f), e2 = __builtin_amdgcn_rcpf(e1);
;                 if (FULL) { const float qx = bf2f(rq[t]); const float qv = qx * fsigmoid(qx);
;                     Q[(tq * 16 + t) * QLD + ch] = f2bf(qv * e1);
;                     Kt[(tq * 16 + t) * QLD + ch] = f2bf(kv[t] * e2); }
;                 ks2[jj] = kv[t] * (total * e2); }
;             ksp[j >> 1] = cvt_pk_bf16(ks2[0], ks2[1]); vip[j >> 1] = (unsigned)ri[j] | ((unsigned)ri[j + 1] << 16);
;         }
;         { LAS u32x4* kp = (LAS u32x4*)(KsT + ch * SLD + tq * 16); kp[0] = (u32x4){ksp[0], ksp[1], ksp[2], ksp[3]}; kp[1] = (u32x4){ksp[4], ksp[5], ksp[6], ksp[7]};
;           LAS u32x4* vp = (LAS u32x4*)(VT + ch * SLD + tq * 16); vp[0] = (u32x4){vip[0], vip[1], vip[2], vip[3]}; vp[1] = (u32x4){vip[4], vip[5], vip[6], vip[7]}; }
;         if (tq == 0) dk[ch] = total;
;         if (c + 1 < SEG_CHUNKS) { const bf16* zr = z + (t0 + 64 + tq * 16) * DIN + hd * 128 + ch;
	v_rcp_f32_e32 v83, v84
	v_mul_f32_e32 v80, v64, v82
	v_mul_f32_e32 v85, v86, v85
	v_mul_f32_e32 v84, v85, v84
	v_cvt_pk_bf16_f32 v80, v80, s0
	v_cvt_pk_bf16_f32 v84, v84, s0
	ds_write_b16 v151, v80 offset:19584
	ds_write_b16 v151, v84 offset:2448
	v_mul_f32_e32 v80, v65, v83
	v_cvt_pk_bf16_f32 v80, v80, s0
	ds_write_b16 v151, v80 offset:19856
	v_pk_mul_f32 v[80:81], v[78:79], v[82:83] op_sel_hi:[0,1]
	v_pk_mul_f32 v[64:65], v[64:65], v[80:81]
	v_lshlrev_b32_e32 v81, 16, v184
	v_mul_f32_e32 v82, 0xbfb8aa3b, v81
	v_exp_f32_e32 v82, v82
	v_cvt_pk_bf16_f32 v64, v64, v65
	v_mul_f32_e32 v65, v112, v108
	v_max_f32_e32 v65, 0x554ad2e, v65
	v_add_f32_e32 v82, 1.0, v82
	v_rcp_f32_e32 v82, v82
	v_rcp_f32_e32 v80, v65
	v_mul_f32_e32 v81, v82, v81
	v_lshlrev_b32_e32 v82, 16, v191
	v_mul_f32_e32 v83, 0xbfb8aa3b, v82
	v_exp_f32_e32 v83, v83
	v_mul_f32_e32 v65, v81, v65
	v_cvt_pk_bf16_f32 v65, v65, s0
	ds_write_b16 v151, v65 offset:2720
	v_add_f32_e32 v83, 1.0, v83
	v_mul_f32_e32 v65, v111, v108
	v_rcp_f32_e32 v83, v83
	v_max_f32_e32 v65, 0x554ad2e, v65
	v_rcp_f32_e32 v81, v65
	v_mul_f32_e32 v76, v74, v80
	v_mul_f32_e32 v82, v83, v82
	v_mul_f32_e32 v65, v82, v65
	v_cvt_pk_bf16_f32 v76, v76, s0
	v_cvt_pk_bf16_f32 v65, v65, s0
	ds_write_b16 v151, v76 offset:20128
	ds_write_b16 v151, v65 offset:2992
	v_pk_mul_f32 v[76:77], v[78:79], v[80:81] op_sel_hi:[0,1]
	v_mul_f32_e32 v65, v75, v81
	v_pk_mul_f32 v[74:75], v[74:75], v[76:77]
	v_lshlrev_b32_e32 v76, 16, v192
	v_mul_f32_e32 v77, 0xbfb8aa3b, v76
	v_exp_f32_e32 v77, v77
	v_cvt_pk_bf16_f32 v65, v65, s0
	ds_write_b16 v151, v65 offset:20400
	v_cvt_pk_bf16_f32 v65, v74, v75
	v_add_f32_e32 v77, 1.0, v77
	v_rcp_f32_e32 v77, v77
	v_mul_f32_e32 v74, v110, v108
	v_max_f32_e32 v75, 0x554ad2e, v74
	v_rcp_f32_e32 v74, v75
	v_mul_f32_e32 v76, v77, v76
	v_lshlrev_b32_e32 v77, 16, v190
	v_mul_f32_e32 v80, 0xbfb8aa3b, v77
	v_exp_f32_e32 v80, v80
	v_mul_f32_e32 v75, v76, v75
	v_cvt_pk_bf16_f32 v75, v75, s0
	ds_write_b16 v151, v75 offset:3264
	v_add_f32_e32 v80, 1.0, v80
	v_mul_f32_e32 v75, v109, v108
	v_rcp_f32_e32 v80, v80
	v_max_f32_e32 v76, 0x554ad2e, v75
	v_rcp_f32_e32 v75, v76
	v_mul_f32_e32 v72, v66, v74
	v_mul_f32_e32 v77, v80, v77
	v_mul_f32_e32 v76, v77, v76
	v_cvt_pk_bf16_f32 v72, v72, s0
	v_cvt_pk_bf16_f32 v76, v76, s0
	ds_write_b16 v151, v72 offset:20672
	ds_write_b16 v151, v76 offset:3536
	v_mul_f32_e32 v72, v67, v75
	v_cvt_pk_bf16_f32 v72, v72, s0
	ds_write_b16 v151, v72 offset:20944
	v_pk_mul_f32 v[72:73], v[78:79], v[74:75] op_sel_hi:[0,1]
	v_pk_mul_f32 v[66:67], v[66:67], v[72:73]
	v_lshlrev_b32_e32 v73, 16, v195
	v_mul_f32_e32 v74, 0xbfb8aa3b, v73
	v_exp_f32_e32 v74, v74
	v_cvt_pk_bf16_f32 v66, v66, v67
	v_mul_f32_e32 v67, v107, v108
	v_max_f32_e32 v67, 0x554ad2e, v67
	v_add_f32_e32 v74, 1.0, v74
	v_rcp_f32_e32 v74, v74
	v_rcp_f32_e32 v72, v67
	v_mul_f32_e32 v73, v74, v73
	v_mul_f32_e32 v67, v73, v67
	v_cvt_pk_bf16_f32 v67, v67, s0
	ds_write_b16 v151, v67 offset:3808
	s_waitcnt vmcnt(0)
	v_lshlrev_b32_e32 v67, 16, v197
	v_mul_f32_e32 v74, 0xbfb8aa3b, v67
	v_exp_f32_e32 v74, v74
	v_rcp_f32_e32 v73, v0
	v_add_f32_e32 v74, 1.0, v74
	v_rcp_f32_e32 v74, v74
	v_pk_mul_f32 v[70:71], v[78:79], v[72:73] op_sel_hi:[0,1]
	v_mul_f32_e32 v67, v74, v67
	v_mul_f32_e32 v0, v67, v0
	v_mul_f32_e32 v67, v68, v72
	v_cvt_pk_bf16_f32 v0, v0, s0
	v_cvt_pk_bf16_f32 v67, v67, s0
	ds_write_b16 v151, v67 offset:21216
	ds_write_b16 v151, v0 offset:4080
	v_mul_f32_e32 v0, v69, v73
	v_cvt_pk_bf16_f32 v0, v0, s0
	v_pk_mul_f32 v[68:69], v[68:69], v[70:71]
	ds_write_b16 v151, v0 offset:21488
	v_cvt_pk_bf16_f32 v67, v68, v69
	ds_write_b128 v124, v[60:63] offset:34816
	ds_write_b128 v124, v[64:67] offset:34832
	ds_write_b128 v124, v[52:55] offset:53248
	ds_write_b128 v124, v[56:59] offset:53264
	s_and_saveexec_b64 vcc, s[10:11]
	ds_write_b32 v125, v78
	s_or_b64 exec, exec, vcc
	s_cmp_eq_u32 s54, 0x2a0000
	s_cbranch_scc1 .LBB0_130
; template <bool FULL>
; __device__ __forceinline__ void hgrn_seg(CArgs& a, LAS unsigned char* lds, int layer, int item, const bf16* z, bf16* mix, float* HS, float* HD) {
;     ...
;         if (c + 1 < SEG_CHUNKS) { const bf16* zr = z + (t0 + 64 + tq * 16) * DIN + hd * 128 + ch;
; #pragma unroll
;             for (int j = 0; j < 16; ++j) { rf[j] = zr[(size_t)j * DIN + ZF]; ri[j] = zr[(size_t)j * DIN + ZI]; if (FULL) rq[j] = zr[(size_t)j * DIN + ZQ]; } }
	v_lshl_add_u64 v[52:53], v[100:101], 0, s[54:55]
	v_add_co_u32_e32 v54, vcc, 0xe560000, v52
	s_nop 1
	v_addc_co_u32_e32 v55, vcc, 0, v53, vcc
	v_add_co_u32_e32 v56, vcc, 0xe561000, v52
	s_nop 1
	v_addc_co_u32_e32 v57, vcc, 0, v53, vcc
	v_add_co_u32_e32 v58, vcc, 0xe562000, v52
	s_nop 1
	v_addc_co_u32_e32 v59, vcc, 0, v53, vcc
	v_add_co_u32_e32 v60, vcc, 0xe563000, v52
	s_nop 1
	v_addc_co_u32_e32 v61, vcc, 0, v53, vcc
	global_load_ushort v117, v[54:55], off offset:1024
	global_load_ushort v216, v[54:55], off offset:2048
	global_load_ushort v116, v[56:57], off offset:3072
	global_load_ushort v217, v[58:59], off
	global_load_ushort v114, v[60:61], off offset:1024
	global_load_ushort v115, v[60:61], off
	global_load_ushort v118, v[56:57], off offset:2048
	global_load_ushort v119, v[54:55], off
	v_add_co_u32_e32 v54, vcc, 0xe564000, v52
	s_nop 1
	v_addc_co_u32_e32 v55, vcc, 0, v53, vcc
	v_add_co_u32_e32 v56, vcc, 0xe565000, v52
	s_nop 1
	v_addc_co_u32_e32 v57, vcc, 0, v53, vcc
	v_add_co_u32_e32 v58, vcc, 0xe566000, v52
	s_nop 1
	v_addc_co_u32_e32 v59, vcc, 0, v53, vcc
	v_add_co_u32_e32 v62, vcc, 0xe567000, v52
	s_nop 1
	v_addc_co_u32_e32 v63, vcc, 0, v53, vcc
	global_load_ushort v218, v[60:61], off offset:2048
	global_load_ushort v120, v[54:55], off offset:3072
	global_load_ushort v219, v[56:57], off
	global_load_ushort v121, v[58:59], off offset:1024
	global_load_ushort v220, v[58:59], off offset:2048
	global_load_ushort v126, v[62:63], off offset:2048
	global_load_ushort v129, v[58:59], off
	global_load_ushort v127, v[54:55], off offset:2048
	v_add_co_u32_e32 v54, vcc, 0xe568000, v52
	s_nop 1
	v_addc_co_u32_e32 v55, vcc, 0, v53, vcc
	v_add_co_u32_e32 v56, vcc, 0xe569000, v52
	s_nop 1
	v_addc_co_u32_e32 v57, vcc, 0, v53, vcc
	v_add_co_u32_e32 v58, vcc, 0xe56a000, v52
	s_nop 1
	v_addc_co_u32_e32 v59, vcc, 0, v53, vcc
	v_add_co_u32_e32 v60, vcc, 0xe56b000, v52
	s_nop 1
	v_addc_co_u32_e32 v61, vcc, 0, v53, vcc
	global_load_ushort v172, v[62:63], off offset:3072
	global_load_ushort v221, v[54:55], off
	global_load_ushort v153, v[56:57], off offset:1024
	global_load_ushort v222, v[56:57], off offset:2048
	global_load_ushort v173, v[58:59], off offset:3072
	global_load_ushort v223, v[60:61], off
	global_load_ushort v175, v[58:59], off offset:2048
	global_load_ushort v171, v[56:57], off
	v_add_co_u32_e32 v54, vcc, 0xe56c000, v52
	s_nop 1
	v_addc_co_u32_e32 v55, vcc, 0, v53, vcc
	v_add_co_u32_e32 v56, vcc, 0xe56d000, v52
	s_nop 1
	v_addc_co_u32_e32 v57, vcc, 0, v53, vcc
	v_add_co_u32_e32 v58, vcc, 0xe56e000, v52
	s_nop 1
	v_addc_co_u32_e32 v59, vcc, 0, v53, vcc
	v_add_co_u32_e32 v60, vcc, 0xe56f000, v52
	s_nop 1
	v_addc_co_u32_e32 v61, vcc, 0, v53, vcc
	global_load_ushort v182, v[54:55], off offset:1024
	global_load_ushort v224, v[54:55], off offset:2048
	global_load_ushort v186, v[56:57], off offset:3072
	global_load_ushort v225, v[58:59], off
	global_load_ushort v183, v[60:61], off offset:1024
	global_load_ushort v184, v[60:61], off
	global_load_ushort v187, v[56:57], off offset:2048
	global_load_ushort v185, v[54:55], off
	v_add_co_u32_e32 v54, vcc, 0xe570000, v52
	s_nop 1
	v_addc_co_u32_e32 v55, vcc, 0, v53, vcc
	v_add_co_u32_e32 v56, vcc, 0xe571000, v52
	s_nop 1
	v_addc_co_u32_e32 v57, vcc, 0, v53, vcc
	v_add_co_u32_e32 v58, vcc, 0xe572000, v52
	s_nop 1
	v_addc_co_u32_e32 v59, vcc, 0, v53, vcc
	v_add_co_u32_e32 v62, vcc, 0xe573000, v52
	s_nop 1
	v_addc_co_u32_e32 v63, vcc, 0, v53, vcc
	global_load_ushort v226, v[60:61], off offset:2048
	s_nop 0
	global_load_ushort v188, v[54:55], off offset:3072
	global_load_ushort v227, v[56:57], off
	global_load_ushort v189, v[58:59], off offset:1024
	global_load_ushort v228, v[58:59], off offset:2048
	global_load_ushort v190, v[62:63], off offset:2048
	global_load_ushort v192, v[58:59], off
	global_load_ushort v191, v[54:55], off offset:2048
	v_add_co_u32_e32 v54, vcc, 0xe574000, v52
	s_nop 1
	v_addc_co_u32_e32 v55, vcc, 0, v53, vcc
	v_add_co_u32_e32 v56, vcc, 0xe575000, v52
	s_nop 1
	v_addc_co_u32_e32 v57, vcc, 0, v53, vcc
	v_add_co_u32_e32 v58, vcc, 0xe576000, v52
	s_nop 1
	v_addc_co_u32_e32 v59, vcc, 0, v53, vcc
	v_add_co_u32_e32 v52, vcc, 0xe577000, v52
	s_nop 1
	v_addc_co_u32_e32 v53, vcc, 0, v53, vcc
	global_load_ushort v196, v[62:63], off offset:3072
	s_nop 0
	global_load_ushort v229, v[54:55], off
	global_load_ushort v193, v[56:57], off offset:1024
	global_load_ushort v230, v[56:57], off offset:2048
	global_load_ushort v194, v[58:59], off offset:3072
	global_load_ushort v231, v[52:53], off
	global_load_ushort v197, v[58:59], off offset:2048
	global_load_ushort v195, v[56:57], off

; __device__ __forceinline__ unsigned cvt_pk_bf16(float lo, float hi) { f32x2_t v = {lo, hi}; bf16x2_t b = __builtin_convertvector(v, bf16x2_t); return __builtin_bit_cast(unsigned, b); }
; #define LAS __attribute__((address_space(3)))
; __device__ __forceinline__ float bf2f(unsigned short h) { return __uint_as_float((unsigned)h << 16); }
; #define BLOCK_SYNC() do { asm volatile("s_waitcnt lgkmcnt(0)" ::: "memory"); __builtin_amdgcn_s_barrier(); asm volatile("" ::: "memory"); } while (0)
; template <bool FULL>
; __device__ __forceinline__ void hgrn_seg(CArgs& a, LAS unsigned char* lds, int layer, int item, const bf16* z, bf16* mix, float* HS, float* HD) {
;     ...
; #pragma unroll
;         for (int j = 0; j < 16; ++j) { const float x = fminf(fmaxf(bf2f(rf[j]), -30.f), 30.f); const float e = __expf(-x), sg = __builtin_amdgcn_rcpf(1.f + e);
;             const float f = lb + oml * sg; run *= f; bl[j] = run; kv[j] = oml * e * sg; }
;     ...
; #pragma unroll
;         for (int kb = 0; kb < 8; ++kb) { const f32x4 d4 = *(const LAS f32x4*)(dk + 16 * kb + 4 * fq);
;             st[kb] = st[kb] * d4;
;             st[kb] = mma16<2>(VT + 16 * wave * SLD, SLD, KsT + 16 * kb * SLD, SLD, st[kb], fr, fq);
;             if (FULL) { u32x2 w; w.x = cvt_pk_bf16(st[kb][0], st[kb][1]); w.y = cvt_pk_bf16(st[kb][2], st[kb][3]);
;                 *(LAS u32x2*)(StT + (16 * wave + fr) * QLD + 16 * kb + 4 * fq) = w; } }
;         BLOCK_SYNC();
.LBB0_167:
	v_add_u32_e32 v52, 0, v0
	s_waitcnt lgkmcnt(0)
	s_barrier
	v_add_u32_e32 v52, 0x1c400, v52
	v_mul_f32_e32 v94, v94, v42
	ds_read_b128 v[46:49], v56 offset:53248
	ds_read_b128 v[42:45], v56 offset:53312
	ds_read_b128 v[62:65], v52
	s_add_u32 s26, s26, 0x60000
	s_addc_u32 s27, s27, 0
	s_cmp_eq_u32 s26, 0x300000
	s_waitcnt lgkmcnt(0)
	v_pk_mul_f32 v[2:3], v[2:3], v[62:63]
	v_pk_mul_f32 v[4:5], v[4:5], v[64:65]
	ds_read_b128 v[62:65], v54 offset:34816
	s_waitcnt lgkmcnt(0)
	v_mfma_f32_16x16x32_bf16 v[2:5], v[62:65], v[46:49], v[2:5]
	ds_read_b128 v[62:65], v54 offset:34880
	s_waitcnt lgkmcnt(0)
	v_mfma_f32_16x16x32_bf16 v[2:5], v[62:65], v[42:45], v[2:5]
	ds_read_b128 v[62:65], v52 offset:64
	s_waitcnt lgkmcnt(0)
	v_pk_mul_f32 v[6:7], v[6:7], v[62:63]
	v_pk_mul_f32 v[8:9], v[8:9], v[64:65]
	ds_read_b128 v[62:65], v54 offset:37120
	s_waitcnt lgkmcnt(0)
	v_mfma_f32_16x16x32_bf16 v[6:9], v[62:65], v[46:49], v[6:9]
	ds_read_b128 v[62:65], v54 offset:37184
	s_waitcnt lgkmcnt(0)
	v_mfma_f32_16x16x32_bf16 v[6:9], v[62:65], v[42:45], v[6:9]
	ds_read_b128 v[62:65], v52 offset:128
	s_waitcnt lgkmcnt(0)
	v_pk_mul_f32 v[18:19], v[18:19], v[62:63]
	v_pk_mul_f32 v[20:21], v[20:21], v[64:65]
	ds_read_b128 v[62:65], v54 offset:39424
	s_waitcnt lgkmcnt(0)
	v_mfma_f32_16x16x32_bf16 v[18:21], v[62:65], v[46:49], v[18:21]
	ds_read_b128 v[62:65], v54 offset:39488
	s_waitcnt lgkmcnt(0)
	v_mfma_f32_16x16x32_bf16 v[18:21], v[62:65], v[42:45], v[18:21]
	ds_read_b128 v[62:65], v52 offset:192
	s_waitcnt lgkmcnt(0)
	v_pk_mul_f32 v[10:11], v[10:11], v[62:63]
	v_pk_mul_f32 v[12:13], v[12:13], v[64:65]
	ds_read_b128 v[62:65], v54 offset:41728
	s_waitcnt lgkmcnt(0)
	v_mfma_f32_16x16x32_bf16 v[10:13], v[62:65], v[46:49], v[10:13]
	ds_read_b128 v[62:65], v54 offset:41792
	s_waitcnt lgkmcnt(0)
	v_mfma_f32_16x16x32_bf16 v[10:13], v[62:65], v[42:45], v[10:13]
	ds_read_b128 v[62:65], v52 offset:256
	s_waitcnt lgkmcnt(0)
	v_pk_mul_f32 v[22:23], v[22:23], v[62:63]
	v_pk_mul_f32 v[24:25], v[24:25], v[64:65]
	ds_read_b128 v[62:65], v54 offset:44032
	s_waitcnt lgkmcnt(0)
	v_mfma_f32_16x16x32_bf16 v[22:25], v[62:65], v[46:49], v[22:25]
	ds_read_b128 v[62:65], v54 offset:44096
	s_waitcnt lgkmcnt(0)
	v_mfma_f32_16x16x32_bf16 v[22:25], v[62:65], v[42:45], v[22:25]
	ds_read_b128 v[62:65], v52 offset:320
	s_waitcnt lgkmcnt(0)
	v_pk_mul_f32 v[14:15], v[14:15], v[62:63]
	v_pk_mul_f32 v[16:17], v[16:17], v[64:65]
	ds_read_b128 v[62:65], v54 offset:46336
	s_waitcnt lgkmcnt(0)
	v_mfma_f32_16x16x32_bf16 v[14:17], v[62:65], v[46:49], v[14:17]
	ds_read_b128 v[62:65], v54 offset:46400
	s_waitcnt lgkmcnt(0)
	v_mfma_f32_16x16x32_bf16 v[14:17], v[62:65], v[42:45], v[14:17]
	ds_read_b128 v[62:65], v52 offset:384
	s_waitcnt lgkmcnt(0)
	v_pk_mul_f32 v[26:27], v[26:27], v[62:63]
	v_pk_mul_f32 v[28:29], v[28:29], v[64:65]
	ds_read_b128 v[62:65], v54 offset:48640
	s_waitcnt lgkmcnt(0)
	v_mfma_f32_16x16x32_bf16 v[26:29], v[62:65], v[46:49], v[26:29]
	ds_read_b128 v[62:65], v54 offset:48704
	s_waitcnt lgkmcnt(0)
	v_mfma_f32_16x16x32_bf16 v[26:29], v[62:65], v[42:45], v[26:29]
	ds_read_b128 v[62:65], v52 offset:448
	s_waitcnt lgkmcnt(0)
	v_pk_mul_f32 v[30:31], v[30:31], v[62:63]
	v_pk_mul_f32 v[32:33], v[32:33], v[64:65]
	ds_read_b128 v[62:65], v54 offset:50944
	s_waitcnt lgkmcnt(0)
	v_mfma_f32_16x16x32_bf16 v[30:33], v[62:65], v[46:49], v[30:33]
	ds_read_b128 v[46:49], v54 offset:51008
	s_waitcnt lgkmcnt(0)
	s_barrier
	s_waitcnt lgkmcnt(0)
	v_mfma_f32_16x16x32_bf16 v[30:33], v[46:49], v[42:45], v[30:33]
	s_cbranch_scc1 .LBB0_172
	s_waitcnt vmcnt(0)
	v_lshl_or_b32 v34, v217, 16, v216
	v_lshl_or_b32 v35, v219, 16, v218
	v_lshl_or_b32 v36, v221, 16, v220
	v_lshl_or_b32 v37, v223, 16, v222
	v_lshl_or_b32 v38, v225, 16, v224
	v_lshl_or_b32 v39, v227, 16, v226
	v_lshl_or_b32 v40, v229, 16, v228
	v_lshl_or_b32 v41, v231, 16, v230
.LBB0_168:
	v_lshlrev_b32_e32 v42, 16, v90
	v_max_f32_e32 v42, v42, v42
	v_med3_f32 v42, v42, s0, v166
	v_mul_f32_e32 v42, 0xbfb8aa3b, v42
	v_exp_f32_e32 v44, v42
	s_nop 0
	v_add_f32_e32 v42, 1.0, v44
	v_rcp_f32_e32 v46, v42
	v_lshlrev_b32_e32 v42, 16, v91
	v_max_f32_e32 v42, v42, v42
	v_med3_f32 v42, v42, s0, v166
	v_mul_f32_e32 v42, 0xbfb8aa3b, v42
	v_exp_f32_e32 v45, v42
	s_nop 0
	v_add_f32_e32 v42, 1.0, v45
	v_rcp_f32_e32 v47, v42
	v_lshlrev_b32_e32 v42, 16, v92
	v_max_f32_e32 v42, v42, v42
	v_med3_f32 v42, v42, s0, v166
	v_mul_f32_e32 v42, 0xbfb8aa3b, v42
	v_exp_f32_e32 v48, v42
	v_pk_fma_f32 v[62:63], v[58:59], v[46:47], v[50:51]
	v_pk_mul_f32 v[44:45], v[58:59], v[44:45]
	v_mov_b32_e32 v52, v62
	v_add_f32_e32 v42, 1.0, v48
	v_rcp_f32_e32 v43, v42
	v_mov_b32_e32 v42, v63
	v_pk_mul_f32 v[44:45], v[44:45], v[46:47]
	v_pk_mul_f32 v[64:65], v[52:53], v[42:43]
	s_nop 0
	v_add_f32_e32 v42, v50, v65
	v_mul_f32_e32 v52, v64, v42
	v_lshlrev_b32_e32 v42, 16, v93
	v_max_f32_e32 v42, v42, v42
	v_med3_f32 v42, v42, s0, v166
	v_mul_f32_e32 v42, 0xbfb8aa3b, v42
	v_exp_f32_e32 v49, v42
	s_nop 0
	v_add_f32_e32 v42, 1.0, v49
	v_rcp_f32_e32 v63, v42
	v_pk_mul_f32 v[48:49], v[58:59], v[48:49]
	v_fma_f32 v42, v53, v63, v50
	v_mul_f32_e32 v57, v52, v42
	s_waitcnt vmcnt(8)
; __device__ __forceinline__ unsigned cvt_pk_bf16(float lo, float hi) { f32x2_t v = {lo, hi}; bf16x2_t b = __builtin_convertvector(v, bf16x2_t); return __builtin_bit_cast(unsigned, b); }
; __device__ __forceinline__ float fsigmoid(float x) { return __builtin_amdgcn_rcpf(1.0f + __expf(-x)); }
; __device__ __forceinline__ float bf2f(unsigned short h) { return __uint_as_float((unsigned)h << 16); }
; __device__ __forceinline__ unsigned short f2bf(float f) { return (unsigned short)(cvt_pk_bf16(f, 0.f) & 0xffffu); }
; #define BLOCK_SYNC() do { asm volatile("s_waitcnt lgkmcnt(0)" ::: "memory"); __builtin_amdgcn_s_barrier(); asm volatile("" ::: "memory"); } while (0)
; template <bool FULL>
; __device__ __forceinline__ void hgrn_seg(CArgs& a, LAS unsigned char* lds, int layer, int item, const bf16* z, bf16* mix, float* HS, float* HD) {
;     ...
;         for (int j = 0; j < 16; ++j) { const float x = fminf(fmaxf(bf2f(rf[j]), -30.f), 30.f); const float e = __expf(-x), sg = __builtin_amdgcn_rcpf(1.f + e);
;             const float f = lb + oml * sg; run *= f; bl[j] = run; kv[j] = oml * e * sg; }
;         seg[tq * 128 + ch] = run;
;         BLOCK_SYNC();
;         float prefix = 1.f, total = 1.f;
; #pragma unroll
;         for (int q = 0; q < 4; ++q) { const float sv = seg[q * 128 + ch]; total *= sv; if (q < tq) prefix *= sv; }
;         dsum *= total;
;         unsigned ksp[8], vip[8];
; #pragma unroll
;         for (int j = 0; j < 16; j += 2) {
;             float ks2[2];
; #pragma unroll
;             for (int jj = 0; jj < 2; ++jj) { const int t = j + jj; const float e1 = fmaxf(prefix * bl[t], 1e-35f), e2 = __builtin_amdgcn_rcpf(e1);
;                 if (FULL) { const float qx = bf2f(rq[t]); const float qv = qx * fsigmoid(qx);
;                     Q[(tq * 16 + t) * QLD + ch] = f2bf(qv * e1);
;                     Kt[(tq * 16 + t) * QLD + ch] = f2bf(kv[t] * e2); }
;                 ks2[jj] = kv[t] * (total * e2); }
;             ksp[j >> 1] = cvt_pk_bf16(ks2[0], ks2[1]); vip[j >> 1] = (unsigned)ri[j] | ((unsigned)ri[j + 1] << 16);
	v_lshlrev_b32_e32 v42, 16, v101
	v_max_f32_e32 v42, v42, v42
	v_med3_f32 v42, v42, s0, v166
	v_mul_f32_e32 v42, 0xbfb8aa3b, v42
	v_exp_f32_e32 v68, v42
	s_nop 0
	v_add_f32_e32 v42, 1.0, v68
	v_rcp_f32_e32 v66, v42
	s_nop 0
	v_fma_f32 v42, v53, v66, v50
	v_mul_f32_e32 v65, v57, v42
	v_lshlrev_b32_e32 v42, 16, v102
	v_max_f32_e32 v42, v42, v42
	v_med3_f32 v42, v42, s0, v166
	v_mul_f32_e32 v42, 0xbfb8aa3b, v42
	v_exp_f32_e32 v69, v42
	s_nop 0
	v_add_f32_e32 v42, 1.0, v69
	v_rcp_f32_e32 v67, v42
	s_nop 0
	v_fma_f32 v42, v53, v67, v50
	v_mul_f32_e32 v113, v65, v42
	v_lshlrev_b32_e32 v42, 16, v103
	v_max_f32_e32 v42, v42, v42
	v_med3_f32 v42, v42, s0, v166
	v_mul_f32_e32 v42, 0xbfb8aa3b, v42
	v_exp_f32_e32 v70, v42
	s_nop 0
	v_add_f32_e32 v42, 1.0, v70
	v_rcp_f32_e32 v72, v42
	s_nop 0
	v_fma_f32 v42, v53, v72, v50
	v_mul_f32_e32 v116, v113, v42
	v_lshlrev_b32_e32 v42, 16, v104
	v_max_f32_e32 v42, v42, v42
	v_med3_f32 v42, v42, s0, v166
	v_mul_f32_e32 v42, 0xbfb8aa3b, v42
	v_exp_f32_e32 v71, v42
	s_nop 0
	v_add_f32_e32 v42, 1.0, v71
	v_rcp_f32_e32 v73, v42
	s_nop 0
	v_fma_f32 v42, v53, v73, v50
	v_mul_f32_e32 v117, v116, v42
	s_waitcnt vmcnt(4)
	v_lshlrev_b32_e32 v42, 16, v105
	v_max_f32_e32 v42, v42, v42
	v_med3_f32 v42, v42, s0, v166
	v_mul_f32_e32 v42, 0xbfb8aa3b, v42
	v_exp_f32_e32 v76, v42
	s_nop 0
	v_add_f32_e32 v42, 1.0, v76
	v_rcp_f32_e32 v74, v42
	s_nop 0
	v_fma_f32 v42, v53, v74, v50
	v_mul_f32_e32 v118, v117, v42
	v_lshlrev_b32_e32 v42, 16, v106
	v_max_f32_e32 v42, v42, v42
	v_med3_f32 v42, v42, s0, v166
	v_mul_f32_e32 v42, 0xbfb8aa3b, v42
	v_exp_f32_e32 v77, v42
	s_nop 0
	v_add_f32_e32 v42, 1.0, v77
	v_rcp_f32_e32 v75, v42
	s_nop 0
	v_fma_f32 v42, v53, v75, v50
	v_mul_f32_e32 v119, v118, v42
	v_lshlrev_b32_e32 v42, 16, v107
	v_max_f32_e32 v42, v42, v42
	v_med3_f32 v42, v42, s0, v166
	v_mul_f32_e32 v42, 0xbfb8aa3b, v42
	v_exp_f32_e32 v80, v42
	s_nop 0
	v_add_f32_e32 v42, 1.0, v80
	v_rcp_f32_e32 v78, v42
	s_nop 0
	v_fma_f32 v42, v53, v78, v50
	v_mul_f32_e32 v120, v119, v42
	v_lshlrev_b32_e32 v42, 16, v108
	v_max_f32_e32 v42, v42, v42
	v_med3_f32 v42, v42, s0, v166
	v_mul_f32_e32 v42, 0xbfb8aa3b, v42
	v_exp_f32_e32 v81, v42
	s_nop 0
	v_add_f32_e32 v42, 1.0, v81
	v_rcp_f32_e32 v79, v42
	s_nop 0
	v_fma_f32 v42, v53, v79, v50
	v_mul_f32_e32 v121, v120, v42
	s_waitcnt vmcnt(0)
	v_lshlrev_b32_e32 v42, 16, v109
	v_max_f32_e32 v42, v42, v42
	v_med3_f32 v42, v42, s0, v166
	v_mul_f32_e32 v42, 0xbfb8aa3b, v42
	v_exp_f32_e32 v82, v42
	s_nop 0
	v_add_f32_e32 v42, 1.0, v82
	v_rcp_f32_e32 v84, v42
	s_nop 0
	v_fma_f32 v42, v53, v84, v50
	v_mul_f32_e32 v122, v121, v42
	v_lshlrev_b32_e32 v42, 16, v110
	v_max_f32_e32 v42, v42, v42
	v_med3_f32 v42, v42, s0, v166
	v_mul_f32_e32 v42, 0xbfb8aa3b, v42
	v_exp_f32_e32 v83, v42
	s_nop 0
	v_add_f32_e32 v42, 1.0, v83
	v_rcp_f32_e32 v85, v42
	s_nop 0
	v_fma_f32 v42, v53, v85, v50
	v_mul_f32_e32 v123, v122, v42
	v_lshlrev_b32_e32 v42, 16, v111
	v_max_f32_e32 v42, v42, v42
	v_med3_f32 v42, v42, s0, v166
	v_mul_f32_e32 v42, 0xbfb8aa3b, v42
	v_exp_f32_e32 v88, v42
	s_nop 0
	v_add_f32_e32 v42, 1.0, v88
	v_rcp_f32_e32 v86, v42
	s_nop 0
	v_fma_f32 v42, v53, v86, v50
	v_mul_f32_e32 v124, v123, v42
	v_lshlrev_b32_e32 v42, 16, v112
	v_max_f32_e32 v42, v42, v42
	v_med3_f32 v42, v42, s0, v166
	v_mul_f32_e32 v42, 0xbfb8aa3b, v42
	v_exp_f32_e32 v89, v42
	s_nop 0
	v_add_f32_e32 v42, 1.0, v89
	v_rcp_f32_e32 v87, v42
	s_nop 0
	v_fma_f32 v42, v53, v87, v50
	v_mul_f32_e32 v125, v124, v42
	ds_write_b32 v97, v125
	s_waitcnt lgkmcnt(0)
	s_barrier
	ds_read2st64_b32 v[114:115], v98 offset1:2
	s_waitcnt lgkmcnt(0)
	v_cndmask_b32_e64 v42, 1.0, v114, s[12:13]
	v_mul_f32_e32 v126, v114, v115
	v_mul_f32_e32 v114, v42, v115
	v_cndmask_b32_e64 v42, v42, v114, s[14:15]
	ds_read2st64_b32 v[114:115], v98 offset0:4 offset1:6
	s_waitcnt lgkmcnt(0)
	v_mul_f32_e32 v126, v126, v114
	v_mul_f32_e32 v114, v114, v42
	v_cndmask_b32_e64 v114, v42, v114, s[16:17]
	v_mul_f32_e32 v42, v126, v115
	v_mul_f32_e32 v115, v115, v114
	v_cndmask_b32_e64 v126, v114, v115, s[18:19]
	v_mul_f32_e32 v62, v62, v126
	v_max_f32_e32 v62, 0x554ad2e, v62
	v_rcp_f32_e32 v114, v62
	v_mul_f32_e32 v62, v64, v126
	v_max_f32_e32 v62, 0x554ad2e, v62
	v_rcp_f32_e32 v115, v62
	v_mov_b32_e32 v62, v43
	v_pk_mul_f32 v[48:49], v[48:49], v[62:63]
	v_pk_mul_f32 v[62:63], v[58:59], v[70:71]
	v_pk_mul_f32 v[46:47], v[42:43], v[114:115] op_sel_hi:[0,1]
	v_pk_mul_f32 v[44:45], v[44:45], v[46:47]
	v_pk_mul_f32 v[62:63], v[62:63], v[72:73]
	v_cvt_pk_bf16_f32 v44, v44, v45
	v_mul_f32_e32 v45, v52, v126
	v_max_f32_e32 v45, 0x554ad2e, v45
	v_rcp_f32_e32 v46, v45
	v_mul_f32_e32 v45, v57, v126
	v_max_f32_e32 v45, 0x554ad2e, v45
	v_rcp_f32_e32 v47, v45
	s_nop 0
	v_pk_mul_f32 v[46:47], v[42:43], v[46:47] op_sel_hi:[0,1]
	v_mul_f32_e32 v43, v65, v126
	v_pk_mul_f32 v[46:47], v[48:49], v[46:47]
	v_max_f32_e32 v43, 0x554ad2e, v43
	v_cvt_pk_bf16_f32 v45, v46, v47
	v_rcp_f32_e32 v46, v43
	v_mul_f32_e32 v43, v113, v126
	v_max_f32_e32 v43, 0x554ad2e, v43
	v_rcp_f32_e32 v47, v43
	v_pk_mul_f32 v[48:49], v[58:59], v[68:69]
	v_pk_mul_f32 v[64:65], v[58:59], v[80:81]
	v_pk_mul_f32 v[48:49], v[48:49], v[66:67]
	v_pk_mul_f32 v[46:47], v[42:43], v[46:47] op_sel_hi:[0,1]
	v_mul_f32_e32 v43, v116, v126
	v_max_f32_e32 v43, 0x554ad2e, v43
	v_pk_mul_f32 v[46:47], v[48:49], v[46:47]
	v_rcp_f32_e32 v48, v43
	v_mul_f32_e32 v43, v117, v126
	v_max_f32_e32 v43, 0x554ad2e, v43
	v_rcp_f32_e32 v49, v43
	v_cvt_pk_bf16_f32 v46, v46, v47
	v_pk_mul_f32 v[64:65], v[64:65], v[78:79]
	v_pk_mul_f32 v[66:67], v[58:59], v[88:89]
	v_pk_mul_f32 v[48:49], v[42:43], v[48:49] op_sel_hi:[0,1]
	v_mul_f32_e32 v43, v118, v126
	v_pk_mul_f32 v[48:49], v[62:63], v[48:49]
; __device__ __forceinline__ unsigned cvt_pk_bf16(float lo, float hi) { f32x2_t v = {lo, hi}; bf16x2_t b = __builtin_convertvector(v, bf16x2_t); return __builtin_bit_cast(unsigned, b); }
; #define LAS __attribute__((address_space(3)))
; template <bool FULL>
; __device__ __forceinline__ void hgrn_seg(CArgs& a, LAS unsigned char* lds, int layer, int item, const bf16* z, bf16* mix, float* HS, float* HD) {
;     ...
;             ksp[j >> 1] = cvt_pk_bf16(ks2[0], ks2[1]); vip[j >> 1] = (unsigned)ri[j] | ((unsigned)ri[j + 1] << 16);
;         }
;         { LAS u32x4* kp = (LAS u32x4*)(KsT + ch * SLD + tq * 16); kp[0] = (u32x4){ksp[0], ksp[1], ksp[2], ksp[3]}; kp[1] = (u32x4){ksp[4], ksp[5], ksp[6], ksp[7]};
;           LAS u32x4* vp = (LAS u32x4*)(VT + ch * SLD + tq * 16); vp[0] = (u32x4){vip[0], vip[1], vip[2], vip[3]}; vp[1] = (u32x4){vip[4], vip[5], vip[6], vip[7]}; }
;         if (tq == 0) dk[ch] = total;
;         if (c + 1 < SEG_CHUNKS) { const bf16* zr = z + (t0 + 64 + tq * 16) * DIN + hd * 128 + ch;
; #pragma unroll
;             for (int j = 0; j < 16; ++j) { rf[j] = zr[(size_t)j * DIN + ZF]; ri[j] = zr[(size_t)j * DIN + ZI]; if (FULL) rq[j] = zr[(size_t)j * DIN + ZQ]; } }
	v_max_f32_e32 v43, 0x554ad2e, v43
	v_cvt_pk_bf16_f32 v47, v48, v49
	v_rcp_f32_e32 v48, v43
	v_mul_f32_e32 v43, v119, v126
	v_max_f32_e32 v43, 0x554ad2e, v43
	v_rcp_f32_e32 v49, v43
	v_pk_mul_f32 v[62:63], v[58:59], v[76:77]
	v_pk_mul_f32 v[66:67], v[66:67], v[86:87]
	v_pk_mul_f32 v[62:63], v[62:63], v[74:75]
	v_pk_mul_f32 v[48:49], v[42:43], v[48:49] op_sel_hi:[0,1]
	v_mul_f32_e32 v43, v120, v126
	v_pk_mul_f32 v[48:49], v[62:63], v[48:49]
	v_max_f32_e32 v43, 0x554ad2e, v43
	v_cvt_pk_bf16_f32 v62, v48, v49
	v_rcp_f32_e32 v48, v43
	v_mul_f32_e32 v43, v121, v126
	v_max_f32_e32 v43, 0x554ad2e, v43
	v_rcp_f32_e32 v49, v43
	s_nop 0
	v_pk_mul_f32 v[48:49], v[42:43], v[48:49] op_sel_hi:[0,1]
	v_mul_f32_e32 v43, v122, v126
	v_pk_mul_f32 v[48:49], v[64:65], v[48:49]
	v_max_f32_e32 v43, 0x554ad2e, v43
	v_cvt_pk_bf16_f32 v63, v48, v49
	v_rcp_f32_e32 v48, v43
	v_mul_f32_e32 v43, v123, v126
	v_max_f32_e32 v43, 0x554ad2e, v43
	v_rcp_f32_e32 v49, v43
	v_pk_mul_f32 v[64:65], v[58:59], v[82:83]
	v_pk_mul_f32 v[48:49], v[42:43], v[48:49] op_sel_hi:[0,1]
	v_pk_mul_f32 v[64:65], v[64:65], v[84:85]
	v_mul_f32_e32 v43, v124, v126
	v_pk_mul_f32 v[48:49], v[64:65], v[48:49]
	v_max_f32_e32 v43, 0x554ad2e, v43
	v_cvt_pk_bf16_f32 v64, v48, v49
	v_rcp_f32_e32 v48, v43
	v_mul_f32_e32 v43, v125, v126
	v_max_f32_e32 v43, 0x554ad2e, v43
	v_rcp_f32_e32 v49, v43
	s_nop 0
	v_pk_mul_f32 v[48:49], v[42:43], v[48:49] op_sel_hi:[0,1]
	v_pk_mul_f32 v[48:49], v[66:67], v[48:49]
	s_nop 0
	v_cvt_pk_bf16_f32 v65, v48, v49
	ds_write_b128 v99, v[44:47] offset:34816
	ds_write_b128 v99, v[62:65] offset:34832
	ds_write_b128 v99, v[34:37] offset:53248
	ds_write_b128 v99, v[38:41] offset:53264
	s_and_saveexec_b64 s[28:29], s[10:11]
	ds_write_b32 v100, v42
	s_or_b64 exec, exec, s[28:29]
	s_cmp_eq_u32 s26, 0x2a0000
	s_cbranch_scc1 .LBB0_167
	v_lshl_add_u64 v[34:35], v[60:61], 0, s[26:27]
	v_add_co_u32_e32 v36, vcc, 0xe560000, v34
	s_nop 1
	v_addc_co_u32_e32 v37, vcc, 0, v35, vcc
	global_load_ushort v90, v[36:37], off offset:1024
	global_load_ushort v216, v[36:37], off offset:2048
	v_add_co_u32_e32 v36, vcc, 0xe561000, v34
	s_nop 1
	v_addc_co_u32_e32 v37, vcc, 0, v35, vcc
	global_load_ushort v91, v[36:37], off offset:3072
	v_add_co_u32_e32 v36, vcc, 0xe562000, v34
	s_nop 1
	v_addc_co_u32_e32 v37, vcc, 0, v35, vcc
	global_load_ushort v217, v[36:37], off
	v_add_co_u32_e32 v36, vcc, 0xe563000, v34
	s_nop 1
	v_addc_co_u32_e32 v37, vcc, 0, v35, vcc
	global_load_ushort v92, v[36:37], off offset:1024
	global_load_ushort v218, v[36:37], off offset:2048
	v_add_co_u32_e32 v36, vcc, 0xe564000, v34
	s_nop 1
	v_addc_co_u32_e32 v37, vcc, 0, v35, vcc
	global_load_ushort v93, v[36:37], off offset:3072
	v_add_co_u32_e32 v36, vcc, 0xe565000, v34
	s_nop 1
	v_addc_co_u32_e32 v37, vcc, 0, v35, vcc
	global_load_ushort v219, v[36:37], off
	v_add_co_u32_e32 v36, vcc, 0xe566000, v34
	s_nop 1
	v_addc_co_u32_e32 v37, vcc, 0, v35, vcc
	global_load_ushort v101, v[36:37], off offset:1024
	global_load_ushort v220, v[36:37], off offset:2048
	v_add_co_u32_e32 v36, vcc, 0xe567000, v34
	s_nop 1
	v_addc_co_u32_e32 v37, vcc, 0, v35, vcc
	global_load_ushort v102, v[36:37], off offset:3072
	v_add_co_u32_e32 v36, vcc, 0xe568000, v34
	s_nop 1
	v_addc_co_u32_e32 v37, vcc, 0, v35, vcc
	global_load_ushort v221, v[36:37], off
	v_add_co_u32_e32 v36, vcc, 0xe569000, v34
	s_nop 1
	v_addc_co_u32_e32 v37, vcc, 0, v35, vcc
	global_load_ushort v103, v[36:37], off offset:1024
	global_load_ushort v222, v[36:37], off offset:2048
	v_add_co_u32_e32 v36, vcc, 0xe56a000, v34
	s_nop 1
	v_addc_co_u32_e32 v37, vcc, 0, v35, vcc
	global_load_ushort v104, v[36:37], off offset:3072
	v_add_co_u32_e32 v36, vcc, 0xe56b000, v34
	s_nop 1
	v_addc_co_u32_e32 v37, vcc, 0, v35, vcc
	global_load_ushort v223, v[36:37], off
	v_add_co_u32_e32 v36, vcc, 0xe56c000, v34
	s_nop 1
	v_addc_co_u32_e32 v37, vcc, 0, v35, vcc
	global_load_ushort v105, v[36:37], off offset:1024
	global_load_ushort v224, v[36:37], off offset:2048
	v_add_co_u32_e32 v36, vcc, 0xe56d000, v34
	s_nop 1
	v_addc_co_u32_e32 v37, vcc, 0, v35, vcc
	global_load_ushort v106, v[36:37], off offset:3072
	v_add_co_u32_e32 v36, vcc, 0xe56e000, v34
	s_nop 1
	v_addc_co_u32_e32 v37, vcc, 0, v35, vcc
	global_load_ushort v225, v[36:37], off
	v_add_co_u32_e32 v36, vcc, 0xe56f000, v34
	s_nop 1
	v_addc_co_u32_e32 v37, vcc, 0, v35, vcc
	global_load_ushort v107, v[36:37], off offset:1024
	global_load_ushort v226, v[36:37], off offset:2048
	v_add_co_u32_e32 v36, vcc, 0xe570000, v34
	s_nop 1
	v_addc_co_u32_e32 v37, vcc, 0, v35, vcc
	global_load_ushort v108, v[36:37], off offset:3072
	v_add_co_u32_e32 v36, vcc, 0xe571000, v34
	s_nop 1
	v_addc_co_u32_e32 v37, vcc, 0, v35, vcc
	global_load_ushort v227, v[36:37], off
	v_add_co_u32_e32 v36, vcc, 0xe572000, v34
	s_nop 1
	v_addc_co_u32_e32 v37, vcc, 0, v35, vcc
	global_load_ushort v109, v[36:37], off offset:1024
	global_load_ushort v228, v[36:37], off offset:2048
	v_add_co_u32_e32 v36, vcc, 0xe573000, v34
	s_nop 1
	v_addc_co_u32_e32 v37, vcc, 0, v35, vcc
	global_load_ushort v110, v[36:37], off offset:3072
	v_add_co_u32_e32 v36, vcc, 0xe574000, v34
	s_nop 1
	v_addc_co_u32_e32 v37, vcc, 0, v35, vcc
	global_load_ushort v229, v[36:37], off
	v_add_co_u32_e32 v36, vcc, 0xe575000, v34
	s_nop 1
	v_addc_co_u32_e32 v37, vcc, 0, v35, vcc
	global_load_ushort v111, v[36:37], off offset:1024
	global_load_ushort v230, v[36:37], off offset:2048
	v_add_co_u32_e32 v36, vcc, 0xe576000, v34
	s_nop 1
	v_addc_co_u32_e32 v37, vcc, 0, v35, vcc
	v_add_co_u32_e32 v34, vcc, 0xe577000, v34
	s_nop 1
	v_addc_co_u32_e32 v35, vcc, 0, v35, vcc
	global_load_ushort v231, v[34:35], off
	global_load_ushort v112, v[36:37], off offset:3072
	s_branch .LBB0_167
